# P9: producers at static priority 1; T-inverse LDS reads of each stage issued together (register renames)
# speedup vs baseline: 1.0013x; 1.0013x over previous
; #define LAS __attribute__((address_space(3)))
; __global__ void __launch_bounds__(512, 2) fwd_megakernel(Params p) {
;     ...
;                         const int pbn = (j + 1) & 1, s0n = ((j + 1) & 1) * 16, tp = tid - 256, t = tp & 15, k0 = 4 * (tp >> 4);
;                         const int ro = (s0n + t) * RS + k0;
;                         const f32x4 e4 = *(const LAS f32x4*)(raw + ro), kk4 = *(const LAS f32x4*)(raw + AS + ro), bb4 = *(const LAS f32x4*)(raw + 2 * AS + ro), kd4 = *(const LAS f32x4*)(raw + 3 * AS + ro), r4 = *(const LAS f32x4*)(raw + 4 * AS + ro), v4 = *(const LAS f32x4*)(raw + 5 * AS + ro);
;                         f32x4 Pt, Pp, iP, PC;
; #pragma unroll
;                         for (int q = 0; q < 4; ++q) { float x = e4[q];
;                             x += dpp_fz<0x111>(x); x += dpp_fz<0x112>(x); x += dpp_fz<0x114>(x); x += dpp_fz<0x118>(x);
;                             const float pt = __expf(-x), sh = dpp_fz<0x111>(pt);
;                             Pt[q] = pt; Pp[q] = (t == 0) ? 1.0f : sh; iP[q] = __builtin_amdgcn_rcpf(pt); PC[q] = iP[q] * __shfl(pt, lane | 15); }
;                         { u32x2 w_;
;                           w_.x = cvt_pk_bf16(-kk4[0] * Pp[0], -kk4[1] * Pp[1]); w_.y = cvt_pk_bf16(-kk4[2] * Pp[2], -kk4[3] * Pp[3]); *(LAS u32x2*)(D64(pbn, 0) + t * LD64 + k0) = w_;
;                           w_.x = cvt_pk_bf16(r4[0] * Pt[0], r4[1] * Pt[1]); w_.y = cvt_pk_bf16(r4[2] * Pt[2], r4[3] * Pt[3]); *(LAS u32x2*)(D64(pbn, 1) + t * LD64 + k0) = w_;
;                           w_.x = cvt_pk_bf16(bb4[0] * iP[0], bb4[1] * iP[1]); w_.y = cvt_pk_bf16(bb4[2] * iP[2], bb4[3] * iP[3]); *(LAS u32x2*)(D64(pbn, 2) + t * LD64 + k0) = w_;
;                           w_.x = cvt_pk_bf16(kd4[0] * iP[0], kd4[1] * iP[1]); w_.y = cvt_pk_bf16(kd4[2] * iP[2], kd4[3] * iP[3]); *(LAS u32x2*)(D64(pbn, 3) + t * LD64 + k0) = w_; }
;                         {
;                             unsigned own[6];
;                             own[0] = cvt_pk_bf16(bb4[0] * PC[0], bb4[1] * PC[1]); own[1] = cvt_pk_bf16(bb4[2] * PC[2], bb4[3] * PC[3]);
;                             own[2] = cvt_pk_bf16(kd4[0] * PC[0], kd4[1] * PC[1]); own[3] = cvt_pk_bf16(kd4[2] * PC[2], kd4[3] * PC[3]);
;                             own[4] = cvt_pk_bf16(v4[0], v4[1]); own[5] = cvt_pk_bf16(v4[2], v4[3]);
;                             const bool ev = (t & 1) == 0;
; #pragma unroll
.Lp9_p_pre:
	s_setprio 1
	s_mov_b32 s25, 1
	v_lshl_or_b32 v28, s25, 4, v74
	v_mad_u32_u24 v28, v28, s62, v81
	v_lshl_add_u32 v32, v28, 2, 0
	ds_read_b128 v[28:31], v32
	ds_read_b128 v[142:145], v32 offset:8704
	ds_read_b128 v[146:149], v32 offset:34816
	ds_read_b128 v[40:43], v32 offset:17408
	ds_read_b128 v[36:39], v32 offset:26112
	ds_read_b128 v[32:35], v32 offset:43520
	v_mov_b32_e32 v251, 0x3020706
	v_mov_b32_e32 v252, 0x5040100
	s_mul_i32 s27, s25, 0x2400
	s_mul_i32 s52, s25, 0x3c00
	v_cndmask_b32_e64 v251, v251, v252, s[4:5]
	v_add3_u32 v141, s27, v116, v117
	v_add_u32_e32 v253, s52, v121
	v_add_u32_e32 v252, 0xec00, v141
	s_waitcnt lgkmcnt(5)
	v_add_f32_dpp v28, v28, v28 row_shr:1 row_mask:0xf bank_mask:0xf bound_ctrl:1
	v_add_f32_dpp v29, v29, v29 row_shr:1 row_mask:0xf bank_mask:0xf bound_ctrl:1
	v_add_f32_dpp v30, v30, v30 row_shr:1 row_mask:0xf bank_mask:0xf bound_ctrl:1
	v_add_f32_dpp v31, v31, v31 row_shr:1 row_mask:0xf bank_mask:0xf bound_ctrl:1
	v_add_f32_dpp v28, v28, v28 row_shr:2 row_mask:0xf bank_mask:0xf bound_ctrl:1
	v_add_f32_dpp v29, v29, v29 row_shr:2 row_mask:0xf bank_mask:0xf bound_ctrl:1
	v_add_f32_dpp v30, v30, v30 row_shr:2 row_mask:0xf bank_mask:0xf bound_ctrl:1
	v_add_f32_dpp v31, v31, v31 row_shr:2 row_mask:0xf bank_mask:0xf bound_ctrl:1
	v_add_f32_dpp v28, v28, v28 row_shr:4 row_mask:0xf bank_mask:0xf bound_ctrl:1
	v_add_f32_dpp v29, v29, v29 row_shr:4 row_mask:0xf bank_mask:0xf bound_ctrl:1
	v_add_f32_dpp v30, v30, v30 row_shr:4 row_mask:0xf bank_mask:0xf bound_ctrl:1
	v_add_f32_dpp v31, v31, v31 row_shr:4 row_mask:0xf bank_mask:0xf bound_ctrl:1
	v_add_f32_dpp v28, v28, v28 row_shr:8 row_mask:0xf bank_mask:0xf bound_ctrl:1
	v_add_f32_dpp v29, v29, v29 row_shr:8 row_mask:0xf bank_mask:0xf bound_ctrl:1
	v_add_f32_dpp v30, v30, v30 row_shr:8 row_mask:0xf bank_mask:0xf bound_ctrl:1
	v_add_f32_dpp v31, v31, v31 row_shr:8 row_mask:0xf bank_mask:0xf bound_ctrl:1
	v_mul_f32_e32 v28, 0xbfb8aa3b, v28
	v_mul_f32_e32 v29, 0xbfb8aa3b, v29
	v_mul_f32_e32 v30, 0xbfb8aa3b, v30
	v_mul_f32_e32 v31, 0xbfb8aa3b, v31
	v_exp_f32_e32 v28, v28
	v_exp_f32_e32 v29, v29
	v_exp_f32_e32 v30, v30
	v_exp_f32_e32 v31, v31
	v_mov_b32_dpp v68, v28 row_shr:1 row_mask:0xf bank_mask:0xf bound_ctrl:1
	v_mov_b32_dpp v69, v29 row_shr:1 row_mask:0xf bank_mask:0xf bound_ctrl:1
	v_mov_b32_dpp v70, v30 row_shr:1 row_mask:0xf bank_mask:0xf bound_ctrl:1
	v_mov_b32_dpp v71, v31 row_shr:1 row_mask:0xf bank_mask:0xf bound_ctrl:1
	v_mov_b32_dpp v247, v28 row_newbcast:15 row_mask:0xf bank_mask:0xf
	v_mov_b32_dpp v248, v29 row_newbcast:15 row_mask:0xf bank_mask:0xf
	v_mov_b32_dpp v249, v30 row_newbcast:15 row_mask:0xf bank_mask:0xf
	v_mov_b32_dpp v250, v31 row_newbcast:15 row_mask:0xf bank_mask:0xf
	v_rcp_f32_e32 v72, v28
	v_rcp_f32_e32 v73, v29
	v_rcp_f32_e32 v150, v30
	v_rcp_f32_e32 v151, v31
	v_cndmask_b32_e64 v68, v68, 1.0, s[2:3]
	v_cndmask_b32_e64 v69, v69, 1.0, s[2:3]
	v_cndmask_b32_e64 v70, v70, 1.0, s[2:3]
	v_cndmask_b32_e64 v71, v71, 1.0, s[2:3]
	s_waitcnt lgkmcnt(4)
	v_mul_f32_e64 v68, v68, -v142
	v_mul_f32_e64 v69, v69, -v143
	v_mul_f32_e64 v70, v70, -v144
	v_mul_f32_e64 v71, v71, -v145
	v_cvt_pk_bf16_f32 v142, v68, v69
	v_cvt_pk_bf16_f32 v143, v70, v71
	ds_write_b64 v141, v[142:143] offset:60416
	s_waitcnt lgkmcnt(4)
	v_mul_f32_e32 v146, v146, v28
	v_mul_f32_e32 v147, v147, v29
	v_mul_f32_e32 v148, v148, v30
	v_mul_f32_e32 v149, v149, v31
	v_cvt_pk_bf16_f32 v144, v146, v147
	v_cvt_pk_bf16_f32 v145, v148, v149
	ds_write_b64 v141, v[144:145] offset:62720
	s_waitcnt lgkmcnt(4)
	v_mul_f32_e32 v68, v40, v72
	v_mul_f32_e32 v69, v41, v73
	v_mul_f32_e32 v70, v42, v150
	v_mul_f32_e32 v71, v43, v151
	v_cvt_pk_bf16_f32 v142, v68, v69
	v_cvt_pk_bf16_f32 v143, v70, v71
	ds_write_b64 v141, v[142:143] offset:65024
	s_waitcnt lgkmcnt(4)
	v_mul_f32_e32 v68, v36, v72
	v_mul_f32_e32 v69, v37, v73
	v_mul_f32_e32 v70, v38, v150
	v_mul_f32_e32 v71, v39, v151
	v_cvt_pk_bf16_f32 v144, v68, v69
	v_cvt_pk_bf16_f32 v145, v70, v71
	ds_write_b64 v252, v[144:145] offset:6912
	v_mul_f32_e32 v247, v72, v247
	v_mul_f32_e32 v248, v73, v248
	v_mul_f32_e32 v249, v150, v249
	v_mul_f32_e32 v250, v151, v250
	v_mul_f32_e32 v40, v40, v247
	v_mul_f32_e32 v41, v41, v248
	v_mul_f32_e32 v42, v42, v249
	v_mul_f32_e32 v43, v43, v250
	v_mul_f32_e32 v36, v36, v247
	v_mul_f32_e32 v37, v37, v248
	v_mul_f32_e32 v38, v38, v249
	v_mul_f32_e32 v39, v39, v250
	v_cvt_pk_bf16_f32 v68, v40, v41
	v_cvt_pk_bf16_f32 v69, v42, v43
	v_cvt_pk_bf16_f32 v70, v36, v37
	v_cvt_pk_bf16_f32 v71, v38, v39
	s_waitcnt lgkmcnt(4)
	v_cvt_pk_bf16_f32 v72, v32, v33
	v_cvt_pk_bf16_f32 v73, v34, v35
	v_mov_b32_dpp v40, v68 quad_perm:[1,0,3,2] row_mask:0xf bank_mask:0xf
	v_mov_b32_dpp v41, v69 quad_perm:[1,0,3,2] row_mask:0xf bank_mask:0xf
	v_mov_b32_dpp v42, v70 quad_perm:[1,0,3,2] row_mask:0xf bank_mask:0xf
	v_mov_b32_dpp v43, v71 quad_perm:[1,0,3,2] row_mask:0xf bank_mask:0xf
	v_mov_b32_dpp v36, v72 quad_perm:[1,0,3,2] row_mask:0xf bank_mask:0xf
	v_mov_b32_dpp v37, v73 quad_perm:[1,0,3,2] row_mask:0xf bank_mask:0xf
	v_perm_b32 v40, v40, v68, v251
	v_perm_b32 v41, v41, v69, v251
	v_perm_b32 v42, v42, v70, v251
	v_perm_b32 v43, v43, v71, v251
	v_perm_b32 v36, v36, v72, v251
	v_perm_b32 v37, v37, v73, v251
	ds_write_b32 v253, v40
	ds_write_b32 v253, v41 offset:160
	ds_write_b32 v253, v42 offset:5120
	ds_write_b32 v253, v43 offset:5280
	ds_write_b32 v253, v36 offset:10240
	ds_write_b32 v253, v37 offset:10400
	s_and_saveexec_b64 s[52:53], s[6:7]
	v_lshl_add_u32 v32, s25, 8, v83
	ds_write_b128 v32, v[28:31]
	s_or_b64 exec, exec, s[52:53]
	s_waitcnt lgkmcnt(0)
	s_barrier

; __global__ void __launch_bounds__(512, 2) fwd_megakernel(Params p) {
;     ...
;                             *(LAS f32x4*)(AabT + fr * 16 + fq * 4) = a;
;                             LDSFENCE();
;                             const int g = (lane >> 3) & 3, c = lane & 7, o = (g == 1 || g == 2) ? 8 : 0;
;                             float U[8];
;                             { const f32x4 h0 = *(const LAS f32x4*)(AabT + c * 16 + 8), h1 = *(const LAS f32x4*)(AabT + c * 16 + 12);
; #pragma unroll
;                               for (int r = 0; r < 8; ++r) { const float rh = r < 4 ? h0[r] : h1[r - 4]; U[r] = (g == 2) ? rh : ((r == c) ? 1.0f : 0.0f); } }
; #pragma unroll
;                             for (int i = 0; i < 7; ++i) {
;                                 const LAS float* colp = AabT + (o + i) * 16 + o;
;                                 const f32x4 c0 = *(const LAS f32x4*)colp, c1 = *(const LAS f32x4*)(colp + 4);
; #pragma unroll
;                                 for (int r = i + 1; r < 8; ++r) U[r] += (r < 4 ? c0[r] : c1[r - 4]) * U[i];
;                             }
;                             if (lane < 24) { LAS float* sc = (g == 0 ? ScT : (g == 1 ? ScT2 : ScM)) + c * 8;
;                                 *(LAS f32x4*)sc = (f32x4){U[0], U[1], U[2], U[3]}; *(LAS f32x4*)(sc + 4) = (f32x4){U[4], U[5], U[6], U[7]}; }
;                             LDSFENCE();
;                             const int r21 = lane >> 3;
;                             const float t11 = ScT[c * 8 + r21], t22 = ScT2[c * 8 + r21];
;                             float t21 = 0.f;
;                             { const f32x4 t0 = *(const LAS f32x4*)(ScT + c * 8), t1 = *(const LAS f32x4*)(ScT + c * 8 + 4);
; #pragma unroll
;                               for (int i = 0; i < 8; ++i) t21 += ScM[i * 8 + r21] * (i < 4 ? t0[i] : t1[i - 4]); }
;                             LAS bf16_t* dst = AMB(pbn, 3);
;                             const float n11 = dpp_f<DPP_XOR1>(t11), n22 = dpp_f<DPP_XOR1>(t22), n21 = dpp_f<DPP_XOR1>(t21);
;                             if ((lane & 1) == 0) {
;                                 *(LAS unsigned*)(dst + r21 * LD32 + c) = cvt_pk_bf16(t11, n11);
;                                 *(LAS unsigned*)(dst + (8 + r21) * LD32 + 8 + c) = cvt_pk_bf16(t22, n22);
;                                 *(LAS unsigned*)(dst + (8 + r21) * LD32 + c) = cvt_pk_bf16(t21, n21);
.Lp9_b859p:
	s_and_b64 vcc, exec, s[54:55]
	s_cbranch_vccz .Lp9_b865p
	v_add_u32_e32 v32, v91, v92
	ds_write_b128 v32, v[28:31]
	s_waitcnt lgkmcnt(0)
	s_and_saveexec_b64 s[54:55], s[10:11]
	s_cbranch_execz .Lp9_b862p
	v_add_u32_e32 v36, s67, v93
	ds_read_b128 v[28:31], v36 offset:32
	v_add_u32_e32 v73, v106, v114
	ds_read_b128 v[32:35], v73
	ds_read_b128 v[36:39], v36 offset:48
	ds_read_b128 v[40:43], v73 offset:16
	ds_read_b128 v[68:71], v73 offset:80
	ds_read_b128 v[142:145], v73 offset:64
	ds_read_b128 v[146:149], v73 offset:144
	ds_read_b128 v[150:153], v73 offset:128
	ds_read_b128 v[156:159], v73 offset:208
	ds_read_b128 v[160:163], v73 offset:272
	ds_read_b128 v[164:167], v73 offset:400
	ds_read_b64 v[154:155], v73 offset:344
	s_waitcnt lgkmcnt(11)
	v_cndmask_b32_e64 v28, v110, v28, s[8:9]
	v_cndmask_b32_e64 v72, v111, v29, s[8:9]
	v_cndmask_b32_e64 v30, v112, v30, s[8:9]
	s_waitcnt lgkmcnt(4)
	v_cndmask_b32_e64 v150, v113, v31, s[8:9]
	v_fmac_f32_e32 v72, v33, v28
	v_fmac_f32_e32 v30, v34, v28
	v_fmac_f32_e32 v150, v35, v28
	v_fmac_f32_e32 v30, v144, v72
	v_fmac_f32_e32 v150, v145, v72
	v_cndmask_b32_e64 v37, v45, v37, s[8:9]
	v_cndmask_b32_e64 v36, v44, v36, s[8:9]
	v_pk_fma_f32 v[36:37], v[40:41], v[28:29], v[36:37] op_sel_hi:[1,0,1]
	v_fmac_f32_e32 v150, v153, v30
	v_pk_fma_f32 v[36:37], v[68:69], v[72:73], v[36:37] op_sel_hi:[1,0,1]
	s_nop 0
	v_pk_fma_f32 v[36:37], v[146:147], v[30:31], v[36:37] op_sel_hi:[1,0,1]
	s_waitcnt lgkmcnt(3)
	v_pk_fma_f32 v[32:33], v[156:157], v[150:151], v[36:37] op_sel_hi:[1,0,1]
	v_cndmask_b32_e64 v37, v47, v39, s[8:9]
	v_cndmask_b32_e64 v36, v46, v38, s[8:9]
	v_pk_fma_f32 v[42:43], v[42:43], v[28:29], v[36:37] op_sel_hi:[1,0,1]
	s_waitcnt lgkmcnt(2)
	v_pk_fma_f32 v[42:43], v[70:71], v[72:73], v[42:43] op_sel_hi:[1,0,1]
	v_fma_f32 v40, v161, v32, v33
	v_pk_fma_f32 v[42:43], v[148:149], v[30:31], v[42:43] op_sel_hi:[1,0,1]
	v_mov_b32_e32 v29, v72
	v_pk_fma_f32 v[34:35], v[158:159], v[150:151], v[42:43] op_sel_hi:[1,0,1]
	v_mov_b32_e32 v31, v150
	v_pk_fma_f32 v[34:35], v[162:163], v[32:33], v[34:35] op_sel_hi:[1,0,1]
	v_mov_b32_e32 v33, v40
	s_waitcnt lgkmcnt(0)
	v_pk_fma_f32 v[34:35], v[154:155], v[40:41], v[34:35] op_sel_hi:[1,0,1]
	v_add_u32_e32 v36, v94, v95
	v_fma_f32 v35, v167, v34, v35
	ds_write_b128 v36, v[28:31]
	ds_write_b128 v36, v[32:35] offset:16
.Lp9_b862p:
	s_or_b64 exec, exec, s[54:55]
	s_waitcnt lgkmcnt(0)
	ds_read2_b32 v[38:39], v99 offset1:8
	ds_read_b128 v[30:33], v98
	ds_read_b32 v29, v96
	ds_read_b32 v28, v97
	ds_read_b128 v[34:37], v98 offset:16
	ds_read2_b32 v[40:41], v99 offset0:16 offset1:24
	ds_read2_b32 v[42:43], v99 offset0:32 offset1:40
	ds_read2_b32 v[168:169], v99 offset0:48 offset1:56
	s_waitcnt lgkmcnt(6)
	v_fma_f32 v30, v38, v30, 0
	v_fmac_f32_e32 v30, v39, v31
	s_waitcnt lgkmcnt(2)
	v_fmac_f32_e32 v30, v40, v32
	v_fmac_f32_e32 v30, v41, v33
	s_waitcnt lgkmcnt(1)
	v_fmac_f32_e32 v30, v42, v34
	v_fmac_f32_e32 v30, v43, v35
	s_waitcnt lgkmcnt(0)
	v_fmac_f32_e32 v30, v168, v36
	v_fmac_f32_e32 v30, v169, v37
	v_mov_b32_e32 v31, 0
	v_mov_b32_e32 v32, 0
	v_mov_b32_e32 v33, 0
	v_mov_b32_dpp v31, v29 quad_perm:[1,0,3,2] row_mask:0xf bank_mask:0xf
	v_mov_b32_dpp v32, v28 quad_perm:[1,0,3,2] row_mask:0xf bank_mask:0xf
	v_mov_b32_dpp v33, v30 quad_perm:[1,0,3,2] row_mask:0xf bank_mask:0xf
	s_and_saveexec_b64 s[54:55], s[4:5]
	s_cbranch_execz .Lp9_b864p
	s_mulk_i32 s74, 0x1400
	v_cvt_pk_bf16_f32 v29, v29, v31
	v_add_u32_e32 v31, s74, v132
	v_cvt_pk_bf16_f32 v28, v28, v32
	ds_write_b32 v31, v28 offset:4496
	v_cvt_pk_bf16_f32 v28, v30, v33
	v_add_u32_e32 v30, 0xe00, v31
	ds_write2_b32 v30, v29, v28 offset0:64 offset1:224

; __global__ void __launch_bounds__(512, 2) fwd_megakernel(Params p) {
;     ...
;                     __syncthreads();
;                 }
.Lp9_t847p:
	s_add_i32 s85, s85, 1
	s_add_i32 s84, s84, -16
	v_add_u32_e32 v140, 16, v140
	s_cmpk_eq_i32 s85, 0x110
	s_waitcnt lgkmcnt(0)
	s_barrier
	s_cbranch_scc0 .Lp9_p_top
	s_setprio 0
	s_branch .LBB0_764
